# v36: v35 + packed f32 multiplies scaling the GLA state accumulators split into scalar v_mul (they sit between MFMAs and feed the next MFMAs)
# baseline (speedup 1.0000x reference)
; #define LAS __attribute__((address_space(3)))
; __device__ __forceinline__ unsigned pk_bf16(float lo, float hi) { f32x2 v; v.x = lo; v.y = hi; const bf16x2_t b = __builtin_convertvector(v, bf16x2_t); return __builtin_bit_cast(unsigned, b); }
; __device__ __forceinline__ void phase_gla(const Frame& F, int l, int gi, int ng, bool last, unsigned* cw) {
;     ...
;             { const f16x8 va = __builtin_bit_cast(f16x8, pv0), vb = __builtin_bit_cast(f16x8, pv1);
; #pragma unroll
;               for (int e = 0; e < 8; e += 2) { const unsigned pa = pk_bf16((float)va[e], (float)va[e + 1]), pb = pk_bf16((float)vb[e], (float)vb[e + 1]);
;                   *(LAS unsigned short*)(lds + GL_VT + ((vs * 16 + e) * 72 + vi) * 2) = (unsigned short)(pa & 0xffffu);
;                   *(LAS unsigned short*)(lds + GL_VT + ((vs * 16 + e + 1) * 72 + vi) * 2) = (unsigned short)(pa >> 16);
;                   *(LAS unsigned short*)(lds + GL_VT + ((vs * 16 + 8 + e) * 72 + vi) * 2) = (unsigned short)(pb & 0xffffu);
;                   *(LAS unsigned short*)(lds + GL_VT + ((vs * 16 + 8 + e + 1) * 72 + vi) * 2) = (unsigned short)(pb >> 16); } }
;     ...
;               for (int e = 0; e < 16; ++e) ob[((e & 3) + 8 * (e >> 2)) * rs] = (f16)oacc[e]; }
; #pragma unroll
;             for (int q = 0; q < 2; ++q) {
; #pragma unroll
;                 for (int g4 = 0; g4 < 4; ++g4) { const f32x4 ev = *(const LAS f32x4*)(lds + GL_EB + (dt * 32 + g4 * 8 + hh * 4) * 4);
; #pragma unroll
;                     for (int e = 0; e < 4; ++e) Sacc[q][g4 * 4 + e] *= ev[e]; }
; #pragma unroll
;                 for (int ks = 0; ks < 4; ++ks) {
;                     const s16x8 a = *(const LAS s16x8*)(lds + GL_KT + ((dt * 32 + r32) * 72 + ks * 16 + hh * 8) * 2);
;                     const s16x8 bb = *(const LAS s16x8*)(lds + GL_VT + (((e2 + q) * 32 + r32) * 72 + ks * 16 + hh * 8) * 2);
;                     Sacc[q] = __builtin_amdgcn_mfma_f32_32x32x16_bf16(a, bb, Sacc[q], 0, 0, 0); }
; #pragma unroll
;                 for (int g4 = 0; g4 < 4; ++g4)
;                     *(LAS u32x2*)(lds + GL_ST + (((e2 + q) * 32 + r32) * 136 + dt * 32 + g4 * 8 + hh * 4) * 2) = (u32x2){pk_bf16(Sacc[q][g4 * 4], Sacc[q][g4 * 4 + 1]), pk_bf16(Sacc[q][g4 * 4 + 2], Sacc[q][g4 * 4 + 3])};
;             }
;             __syncthreads();
.LBB0_643:
	s_waitcnt lgkmcnt(7)
	v_mul_f32_e32 v2, v2, v230
	v_mul_f32_e32 v3, v3, v231
	v_mul_f32_e32 v4, v4, v232
	v_mul_f32_e32 v5, v5, v233
	v_mul_f32_e32 v18, v18, v230
	v_mul_f32_e32 v19, v19, v231
	v_mul_f32_e32 v20, v20, v232
	v_mul_f32_e32 v21, v21, v233
	s_waitcnt lgkmcnt(6)
	v_mul_f32_e32 v6, v6, v242
	v_mul_f32_e32 v7, v7, v243
	v_mul_f32_e32 v8, v8, v244
	v_mul_f32_e32 v9, v9, v245
	v_mul_f32_e32 v22, v22, v242
	v_mul_f32_e32 v23, v23, v243
	v_mul_f32_e32 v24, v24, v244
	v_mul_f32_e32 v25, v25, v245
	s_waitcnt lgkmcnt(5)
	v_mul_f32_e32 v10, v10, v246
	v_mul_f32_e32 v11, v11, v247
	v_mul_f32_e32 v12, v12, v248
	v_mul_f32_e32 v13, v13, v249
	v_mul_f32_e32 v26, v26, v246
	v_mul_f32_e32 v27, v27, v247
	v_mul_f32_e32 v28, v28, v248
	v_mul_f32_e32 v29, v29, v249
	s_waitcnt lgkmcnt(4)
	v_mul_f32_e32 v14, v14, v62
	v_mul_f32_e32 v15, v15, v63
	v_mul_f32_e32 v16, v16, v64
	v_mul_f32_e32 v17, v17, v65
	v_mul_f32_e32 v30, v30, v62
	v_mul_f32_e32 v31, v31, v63
	v_mul_f32_e32 v32, v32, v64
	v_mul_f32_e32 v33, v33, v65
	v_add_u32_e32 v184, s0, v107
	v_readlane_b32 s0, v254, 16
	v_ashrrev_i32_e32 v185, 31, v184
	v_lshlrev_b64 v[184:185], 11, v[184:185]
	v_lshl_add_u64 v[184:185], v[112:113], 0, v[184:185]
	v_add_u32_e32 v189, s0, v130
	v_readlane_b32 s0, v254, 17
	ds_read_b128 v[192:195], v189
	ds_read_b128 v[200:203], v173
	ds_read_b128 v[214:217], v189 offset:32
	ds_read_b128 v[218:221], v173 offset:32
	ds_read_b128 v[222:225], v189 offset:64
	ds_read_b128 v[226:229], v173 offset:64
	ds_read_b128 v[230:233], v189 offset:96
	ds_read_b128 v[242:245], v173 offset:96
	v_cvt_f16_f32_e32 v188, v34
	global_store_short v[184:185], v188, off
	v_lshl_add_u64 v[186:187], s[8:9], 1, v[184:185]
	v_cvt_f16_f32_e32 v190, v35
	global_store_short v[186:187], v190, off
	v_lshl_add_u64 v[186:187], v[186:187], 0, s[10:11]
	v_cvt_f16_f32_e32 v188, v36
	global_store_short v[186:187], v188, off
	v_lshl_add_u64 v[186:187], v[186:187], 0, s[10:11]
	v_cvt_f16_f32_e32 v190, v37
	global_store_short v[186:187], v190, off
	v_lshl_add_u64 v[186:187], v[186:187], 0, s[86:87]
	s_waitcnt lgkmcnt(7)
	v_mfma_f32_32x32x16_bf16 v[2:17], v[50:53], v[192:195], v[2:17]
	v_cvt_f16_f32_e32 v188, v38
	global_store_short v[186:187], v188, off
	v_lshl_add_u64 v[186:187], v[186:187], 0, s[10:11]
	v_cvt_f16_f32_e32 v190, v39
	global_store_short v[186:187], v190, off
	s_waitcnt lgkmcnt(6)
	v_mfma_f32_32x32x16_bf16 v[18:33], v[50:53], v[200:203], v[18:33]
	v_lshl_add_u64 v[186:187], v[186:187], 0, s[10:11]
	v_cvt_f16_f32_e32 v188, v40
	global_store_short v[186:187], v188, off
	v_lshl_add_u64 v[186:187], v[186:187], 0, s[10:11]
	v_cvt_f16_f32_e32 v190, v41
	s_waitcnt lgkmcnt(5)
	v_mfma_f32_32x32x16_bf16 v[2:17], v[54:57], v[214:217], v[2:17]
	global_store_short v[186:187], v190, off
	v_lshl_add_u64 v[186:187], v[186:187], 0, s[86:87]
	v_cvt_f16_f32_e32 v188, v42
	global_store_short v[186:187], v188, off
	v_lshl_add_u64 v[186:187], v[186:187], 0, s[10:11]
	s_waitcnt lgkmcnt(4)
	v_mfma_f32_32x32x16_bf16 v[18:33], v[54:57], v[218:221], v[18:33]
	v_cvt_f16_f32_e32 v190, v43
	global_store_short v[186:187], v190, off
	v_lshl_add_u64 v[186:187], v[186:187], 0, s[10:11]
	v_cvt_f16_f32_e32 v188, v44
	global_store_short v[186:187], v188, off
	s_waitcnt lgkmcnt(3)
	v_mfma_f32_32x32x16_bf16 v[2:17], v[58:61], v[222:225], v[2:17]
	v_lshl_add_u64 v[186:187], v[186:187], 0, s[10:11]
	v_cvt_f16_f32_e32 v190, v45
	global_store_short v[186:187], v190, off
	v_lshl_add_u64 v[186:187], v[186:187], 0, s[86:87]
	v_cvt_f16_f32_e32 v188, v46
	s_waitcnt lgkmcnt(2)
	v_mfma_f32_32x32x16_bf16 v[18:33], v[58:61], v[226:229], v[18:33]
	global_store_short v[186:187], v188, off
	v_lshl_add_u64 v[186:187], v[186:187], 0, s[10:11]
	v_cvt_f16_f32_e32 v190, v47
	global_store_short v[186:187], v190, off
	v_lshl_add_u64 v[186:187], v[186:187], 0, s[10:11]
	s_waitcnt lgkmcnt(1)
	v_mfma_f32_32x32x16_bf16 v[2:17], v[180:183], v[230:233], v[2:17]
	v_cvt_f16_f32_e32 v188, v48
	global_store_short v[186:187], v188, off
	v_lshl_add_u64 v[186:187], v[186:187], 0, s[10:11]
	v_cvt_f16_f32_e32 v190, v49
	global_store_short v[186:187], v190, off
	s_waitcnt lgkmcnt(0)
	v_mfma_f32_32x32x16_bf16 v[18:33], v[180:183], v[242:245], v[18:33]
	v_add_u32_e32 v36, s33, v131
	s_nop 10
	v_cvt_pk_bf16_f32 v34, v2, v3
	v_cvt_pk_bf16_f32 v35, v4, v5
	ds_write_b64 v36, v[34:35]
	v_cvt_pk_bf16_f32 v34, v6, v7
	v_cvt_pk_bf16_f32 v35, v8, v9
	v_add_u32_e32 v36, s0, v131
	ds_write_b64 v36, v[34:35]
	v_cvt_pk_bf16_f32 v34, v10, v11
	v_cvt_pk_bf16_f32 v35, v12, v13
	v_add_u32_e32 v36, s95, v131
	ds_write_b64 v36, v[34:35]
	v_cvt_pk_bf16_f32 v34, v14, v15
	v_cvt_pk_bf16_f32 v35, v16, v17
	v_add_u32_e32 v36, s89, v131
	ds_write_b64 v36, v[34:35]
	v_add_u32_e32 v36, s33, v132
	v_cvt_pk_bf16_f32 v34, v18, v19
	v_cvt_pk_bf16_f32 v35, v20, v21
	ds_write_b64 v36, v[34:35]
	v_cvt_pk_bf16_f32 v34, v22, v23
	v_cvt_pk_bf16_f32 v35, v24, v25
	v_add_u32_e32 v36, s0, v132
	ds_write_b64 v36, v[34:35]
	v_cvt_pk_bf16_f32 v34, v26, v27
	v_cvt_pk_bf16_f32 v35, v28, v29
	v_add_u32_e32 v36, s95, v132
	ds_write_b64 v36, v[34:35]
	v_cvt_pk_bf16_f32 v34, v30, v31
	v_cvt_pk_bf16_f32 v35, v32, v33
	v_add_u32_e32 v36, s89, v132
	ds_write_b64 v36, v[34:35]
	s_waitcnt vmcnt(16)
	v_cvt_pk_f16_f32 v192, v118, v119
	v_cvt_f32_f16_sdwa v34, v86 dst_sel:DWORD dst_unused:UNUSED_PAD src0_sel:WORD_1
	v_cvt_f32_f16_e32 v35, v86
	v_cvt_f32_f16_e32 v36, v90
	v_cvt_pk_bf16_f32 v184, v35, v34
	v_cvt_f32_f16_sdwa v35, v90 dst_sel:DWORD dst_unused:UNUSED_PAD src0_sel:WORD_1
	v_cvt_pk_bf16_f32 v185, v36, v35
	v_cvt_f32_f16_sdwa v34, v87 dst_sel:DWORD dst_unused:UNUSED_PAD src0_sel:WORD_1
	v_cvt_f32_f16_e32 v35, v87
	v_cvt_f32_f16_e32 v36, v91
	v_cvt_pk_bf16_f32 v186, v35, v34
	v_cvt_f32_f16_sdwa v35, v91 dst_sel:DWORD dst_unused:UNUSED_PAD src0_sel:WORD_1
	v_cvt_pk_bf16_f32 v187, v36, v35
	v_cvt_f32_f16_sdwa v34, v88 dst_sel:DWORD dst_unused:UNUSED_PAD src0_sel:WORD_1
	v_cvt_f32_f16_e32 v35, v88
	v_cvt_f32_f16_e32 v36, v92
	v_cvt_pk_bf16_f32 v188, v35, v34
	v_cvt_f32_f16_sdwa v35, v92 dst_sel:DWORD dst_unused:UNUSED_PAD src0_sel:WORD_1
	v_cvt_pk_bf16_f32 v189, v36, v35
	v_cvt_f32_f16_sdwa v34, v89 dst_sel:DWORD dst_unused:UNUSED_PAD src0_sel:WORD_1
	v_cvt_f32_f16_e32 v35, v89
	v_cvt_f32_f16_e32 v36, v93
	v_cvt_pk_bf16_f32 v190, v35, v34
	v_cvt_f32_f16_sdwa v35, v93 dst_sel:DWORD dst_unused:UNUSED_PAD src0_sel:WORD_1
	v_cvt_pk_bf16_f32 v191, v36, v35
	s_add_i32 s37, s37, -1
	s_add_i32 s7, s7, 1
	s_cmp_eq_u32 s7, 64
	s_waitcnt lgkmcnt(0)
	s_barrier
	s_cbranch_scc1 .LBB0_666
	.p2align	6
